# prep GDN fast path: next iteration's row loads issued right after the current raw data are converted (software prefetch), on top of v68
# baseline (speedup 1.0000x reference)
.LBB0_1878:
	v_readlane_b32 s0, v251, 29
	v_readlane_b32 s1, v251, 30
	s_mov_b32 s2, s0
	s_mul_hi_i32 s9, s0, 0x120000
	v_readlane_b32 s0, v251, 23
	s_cmp_gt_i32 s0, 0x87ff
	s_mul_i32 s8, s2, 0x120000
	v_readlane_b32 s1, v251, 24
	s_cbranch_scc1 .LBB0_1931
	v_readlane_b32 s0, v251, 29
	v_readlane_b32 s1, v251, 30
	s_mul_i32 s2, s0, 0x3000
	s_lshl_b32 s4, s0, 3
	s_ashr_i32 s3, s2, 31
	s_ashr_i32 s5, s4, 31
	s_lshl_b64 s[0:1], s[8:9], 2
	s_waitcnt lgkmcnt(0)
	s_add_u32 s0, s16, s0
	s_addc_u32 s1, s17, s1
	s_lshl_b64 s[2:3], s[2:3], 2
	s_add_u32 s10, s22, s2
	s_addc_u32 s11, s23, s3
	s_lshl_b64 s[2:3], s[4:5], 2
	s_add_u32 s12, s24, s2
	s_addc_u32 s13, s25, s3
	s_add_u32 s16, s28, s2
	s_addc_u32 s17, s29, s3
	v_readlane_b32 s2, v251, 1
	v_readlane_b32 s3, v251, 2
	s_add_u32 s22, s2, 0x2c900000
	s_addc_u32 s23, s3, 0
	s_add_u32 s24, s2, 0x2eb00000
	s_addc_u32 s25, s3, 0
	s_add_u32 s28, s2, 0x30d00000
	s_addc_u32 s29, s3, 0
	s_add_u32 s4, s2, 0x32f00000
	s_addc_u32 s5, s3, 0
	s_add_u32 s30, s10, 0x3000
	s_addc_u32 s31, s11, 0
	s_add_u32 s34, s10, 0x6000
	s_addc_u32 s35, s11, 0
	s_waitcnt vmcnt(0)
	v_and_b32_e32 v4, 64, v206
	s_add_u32 s36, s10, 0x9000
	v_xor_b32_e32 v3, 16, v206
	v_add_u32_e32 v4, 64, v4
	v_readlane_b32 s6, v251, 0
	s_addc_u32 s37, s11, 0
	v_cmp_lt_i32_e32 vcc, v3, v4
	s_lshl_b32 s6, s6, 1
	v_readlane_b32 s7, v252, 51
	v_and_b32_e32 v2, 31, v219
	v_cndmask_b32_e32 v3, v206, v3, vcc
	s_add_i32 s18, s7, s6
	v_readlane_b32 s6, v251, 23
	v_lshrrev_b32_e32 v0, 5, v138
	v_lshlrev_b32_e32 v72, 2, v2
	v_lshlrev_b32_e32 v73, 2, v3
	v_cmp_eq_u32_e64 s[2:3], 0, v2
	s_mov_b32 s19, s6
	v_readlane_b32 s7, v251, 24
	v_and_or_b32 v84, s18, 6, v0
	v_mov_b32_e32 v191, 0xffff0000
	v_lshl_or_b32 v85, v84, 7, v72
	v_lshlrev_b32_e32 v192, 3, v84
	v_lshlrev_b32_e32 v193, 2, v84
	v_lshlrev_b32_e32 v86, 2, v85
	v_lshlrev_b32_e32 v89, 1, v85
	v_lshlrev_b32_e32 v190, 1, v84
	v_add_u32_e32 v87, 0x1000, v86
	v_add_u32_e32 v88, 0x2000, v86
	v_add_u32_e32 v90, 0x800, v89
	v_add_u32_e32 v91, 0x1000, v89
	v_add_u32_e32 v190, 0x2000, v190
	global_load_dword v188, v193, s[12:13]
	global_load_dword v189, v193, s[16:17]
	global_load_dwordx4 v[140:143], v86, s[10:11]
	global_load_dwordx4 v[144:147], v87, s[10:11]
	global_load_dwordx4 v[148:151], v88, s[10:11]
	global_load_dwordx4 v[152:155], v86, s[30:31]
	global_load_dwordx4 v[156:159], v87, s[30:31]
	global_load_dwordx4 v[160:163], v88, s[30:31]
	global_load_dwordx4 v[164:167], v86, s[34:35]
	global_load_dwordx4 v[168:171], v87, s[34:35]
	global_load_dwordx4 v[172:175], v88, s[34:35]
	global_load_dwordx4 v[176:179], v86, s[36:37]
	global_load_dwordx4 v[180:183], v87, s[36:37]
	global_load_dwordx4 v[184:187], v88, s[36:37]
	s_waitcnt vmcnt(0)
	s_mov_b32 s41, 0
	v_mul_f32_e32 v188, 0x3fb8aa3b, v188
	v_exp_f32_e32 v188, v188
	s_branch .LBB0_1881

.LBB0_1881:
	s_ashr_i32 s40, s19, 2
	s_cmpk_gt_i32 s40, 0x1fff
	s_cselect_b32 s51, 3, 0x7ff
	s_cselect_b32 s52, 1, 0
	s_and_b32 s51, s40, s51
	s_add_i32 s6, s40, -3
	v_readlane_b32 s48, v251, 16
	v_readlane_b32 s49, v251, 17
	s_mul_hi_i32 s7, s6, 0x3c00
	s_mulk_i32 s6, 0x3c00
	s_add_u32 s6, s48, s6
	s_addc_u32 s7, s49, s7
	s_add_u32 s6, s6, 0x1a00
	s_addc_u32 s7, s7, 0
	s_add_i32 s53, s40, 0xffffe000
	s_lshr_b32 s53, s53, 2
	s_mul_i32 s54, s53, 0x9000
	s_mul_hi_u32 s55, s53, 0x9000
	s_add_u32 s54, s0, s54
	s_addc_u32 s55, s1, s55
	s_cmp_eq_u32 s41, 1
	s_cbranch_scc1 .Lgdp_prefetched
	s_add_i32 s26, s51, 0
	s_cmp_lt_u32 s26, 3
	s_cbranch_scc1 .Lgdp_t0_early
	global_load_dwordx2 v[2:3], v89, s[6:7]
	global_load_dwordx2 v[4:5], v90, s[6:7]
	global_load_dwordx2 v[6:7], v91, s[6:7]
	s_branch .Lgdp_t0_done

.Lgdp_t3_done:
	global_load_ushort v26, v190, s[6:7]
	global_load_ushort v27, v190, s[6:7] offset:16
	s_waitcnt vmcnt(0)
	s_branch .Lgdp_conv
.Lgdp_prefetched:
	s_waitcnt vmcnt(5)
	v_mov_b32_e32 v26, v57
	v_mov_b32_e32 v27, v58
.Lgdp_conv:
	s_lshl_b32 s44, s40, 12
	v_add_u32_e32 v56, s44, v86
	s_add_i32 s26, s51, 0
	s_cmp_lt_u32 s26, 3
	s_cbranch_scc1 .Lgdp_c0_early
	v_lshlrev_b32_e32 v92, 16, v2
	v_and_b32_e32 v93, v191, v2
	v_lshlrev_b32_e32 v94, 16, v3
	v_and_b32_e32 v95, v191, v3
	v_lshlrev_b32_e32 v96, 16, v4
	v_and_b32_e32 v97, v191, v4
	v_lshlrev_b32_e32 v98, 16, v5
	v_and_b32_e32 v99, v191, v5
	v_lshlrev_b32_e32 v100, 16, v6
	v_and_b32_e32 v101, v191, v6
	v_lshlrev_b32_e32 v102, 16, v7
	v_and_b32_e32 v103, v191, v7
	s_branch .Lgdp_c0_done

.Lgdp_c3_done:
	s_mov_b32 s41, 0
	s_add_i32 s26, s19, s50
	s_cmp_gt_i32 s26, 0x87ff
	s_cbranch_scc1 .Lgdp_nopf
	s_ashr_i32 s26, s26, 2
	s_cmpk_gt_i32 s26, 0x1fff
	s_cbranch_scc1 .Lgdp_nopf
	s_and_b32 s27, s26, 0x7ff
	s_cmp_lt_u32 s27, 3
	s_cbranch_scc1 .Lgdp_nopf
	s_add_i32 s26, s26, -3
	s_mul_hi_i32 s27, s26, 0x3c00
	s_mulk_i32 s26, 0x3c00
	s_add_u32 s26, s48, s26
	s_addc_u32 s27, s49, s27
	s_add_u32 s26, s26, 0x1a00
	s_addc_u32 s27, s27, 0
	global_load_dwordx2 v[2:3], v89, s[26:27]
	global_load_dwordx2 v[4:5], v90, s[26:27]
	global_load_dwordx2 v[6:7], v91, s[26:27]
	s_add_u32 s26, s26, 0x3c00
	s_addc_u32 s27, s27, 0
	global_load_dwordx2 v[8:9], v89, s[26:27]
	global_load_dwordx2 v[10:11], v90, s[26:27]
	global_load_dwordx2 v[12:13], v91, s[26:27]
	s_add_u32 s26, s26, 0x3c00
	s_addc_u32 s27, s27, 0
	global_load_dwordx2 v[14:15], v89, s[26:27]
	global_load_dwordx2 v[16:17], v90, s[26:27]
	global_load_dwordx2 v[18:19], v91, s[26:27]
	s_add_u32 s26, s26, 0x3c00
	s_addc_u32 s27, s27, 0
	global_load_dwordx2 v[20:21], v89, s[26:27]
	global_load_dwordx2 v[22:23], v90, s[26:27]
	global_load_dwordx2 v[24:25], v91, s[26:27]
	global_load_ushort v57, v190, s[26:27]
	global_load_ushort v58, v190, s[26:27] offset:16
	s_mov_b32 s41, 1
